# v118 + P11 final epilogue residual part: x2 loads of 7 of the 8 row blocks issued together at the top (counted waits)
# baseline (speedup 1.0000x reference)
.LBB0_1452:
	v_mov_b32_e32 v140, v165
	v_mov_b32_e32 v160, v163
	v_mov_b32_e32 v141, v162
	v_mov_b32_e32 v161, v164
	s_lshl_b32 s0, s2, 8
	s_add_i32 s0, s0, s35
	v_add_u32_e32 v140, s0, v160
	s_lshl_b32 s0, s24, 8
	s_or_b32 s0, s0, s36
	v_ashrrev_i32_e32 v141, 31, v140
	v_lshl_add_u32 v142, v161, 3, s0
	v_lshlrev_b64 v[144:145], 12, v[140:141]
	v_lshl_add_u64 v[144:145], s[62:63], 0, v[144:145]
	v_ashrrev_i32_e32 v143, 31, v142
	v_lshl_add_u64 v[148:149], v[142:143], 1, v[144:145]
	s_mov_b32 s98, 0x10000
	s_mov_b32 s99, 0
	global_load_dwordx4 v[190:193], v[148:149], off
	global_load_dwordx4 v[194:197], v[148:149], off offset:256
	v_lshl_add_u64 v[226:227], v[148:149], 0, s[98:99]
	global_load_dwordx4 v[198:201], v[226:227], off
	global_load_dwordx4 v[202:205], v[226:227], off offset:256
	v_lshl_add_u64 v[226:227], v[226:227], 0, s[98:99]
	global_load_dwordx4 v[206:209], v[226:227], off
	global_load_dwordx4 v[210:213], v[226:227], off offset:256
	v_lshl_add_u64 v[226:227], v[226:227], 0, s[98:99]
	global_load_dwordx4 v[214:217], v[226:227], off
	global_load_dwordx4 v[218:221], v[226:227], off offset:256
	s_mov_b32 s98, 0x50000
	v_lshl_add_u64 v[226:227], v[226:227], 0, s[98:99]
	s_mov_b32 s98, 0x10000
	global_load_dwordx4 v[222:225], v[226:227], off
	global_load_dwordx4 v[230:233], v[226:227], off offset:256
	v_lshl_add_u64 v[226:227], v[226:227], 0, s[98:99]
	global_load_dwordx4 v[234:237], v[226:227], off
	global_load_dwordx4 v[238:241], v[226:227], off offset:256
	v_lshl_add_u64 v[226:227], v[226:227], 0, s[98:99]
	global_load_dwordx4 v[242:245], v[226:227], off
	global_load_dwordx4 v[246:249], v[226:227], off offset:256
	s_nop 0
	s_nop 0
	v_and_b32_e32 v153, 64, v170
	v_xor_b32_e32 v152, 16, v170
	v_add_u32_e32 v173, 64, v153
	v_cmp_lt_i32_e32 vcc, v152, v173
	s_waitcnt vmcnt(12)
	v_and_b32_e32 v153, 0xffff0000, v190
	v_cndmask_b32_e32 v152, v170, v152, vcc
	v_lshlrev_b32_e32 v172, 2, v152
	v_lshlrev_b32_e32 v152, 16, v190
	v_lshlrev_b32_e32 v144, 16, v191
	v_and_b32_e32 v145, 0xffff0000, v191
	v_lshlrev_b32_e32 v154, 16, v192
	v_and_b32_e32 v155, 0xffff0000, v192
	v_lshlrev_b32_e32 v158, 16, v194
	v_and_b32_e32 v159, 0xffff0000, v194
	v_lshlrev_b32_e32 v148, 16, v195
	v_and_b32_e32 v149, 0xffff0000, v195
	v_lshlrev_b32_e32 v156, 16, v193
	v_and_b32_e32 v157, 0xffff0000, v193
	v_lshlrev_b32_e32 v174, 16, v196
	v_and_b32_e32 v175, 0xffff0000, v196
	v_pk_add_f32 v[144:145], v[126:127], v[144:145]
	v_pk_add_f32 v[146:147], v[124:125], v[152:153]
	v_pk_add_f32 v[126:127], v[120:121], v[154:155]
	v_pk_add_f32 v[118:119], v[118:119], v[148:149]
	v_pk_add_f32 v[120:121], v[116:117], v[158:159]
	v_lshlrev_b32_e32 v150, 16, v197
	v_and_b32_e32 v151, 0xffff0000, v197
	v_pk_add_f32 v[116:117], v[112:113], v[174:175]
	v_mul_f32_e32 v112, v147, v147
	v_mul_f32_e32 v113, v145, v145
	v_mul_f32_e32 v148, v121, v121
	v_mul_f32_e32 v149, v119, v119
	v_pk_add_f32 v[124:125], v[122:123], v[156:157]
	v_pk_add_f32 v[114:115], v[114:115], v[150:151]
	v_mul_f32_e32 v122, v127, v127
	v_mul_f32_e32 v150, v117, v117
	v_fmac_f32_e32 v112, v146, v146
	v_fmac_f32_e32 v113, v144, v144
	v_fmac_f32_e32 v148, v120, v120
	v_fmac_f32_e32 v149, v118, v118
	v_mul_f32_e32 v123, v125, v125
	v_mul_f32_e32 v151, v115, v115
	v_fmac_f32_e32 v122, v126, v126
	v_fmac_f32_e32 v150, v116, v116
	v_add_f32_e32 v112, v112, v113
	v_add_f32_e32 v113, v148, v149
	v_fmac_f32_e32 v123, v124, v124
	v_fmac_f32_e32 v151, v114, v114
	v_add_f32_e32 v112, v122, v112
	v_add_f32_e32 v113, v150, v113
	v_add_f32_e32 v112, v123, v112
	v_add_f32_e32 v113, v151, v113
	v_add_f32_e32 v112, v112, v113
	ds_bpermute_b32 v113, v172, v112
	v_xor_b32_e32 v122, 32, v170
	v_cmp_lt_i32_e32 vcc, v122, v173
	s_nop 1
	v_cndmask_b32_e32 v122, v170, v122, vcc
	v_lshlrev_b32_e32 v173, 2, v122
	s_waitcnt lgkmcnt(0)
	v_add_f32_e32 v122, v112, v113
	ds_bpermute_b32 v123, v173, v122
	v_cmp_eq_u32_e32 vcc, 0, v161
	v_lshl_add_u64 v[112:113], v[140:141], 2, s[6:7]
	s_and_saveexec_b64 s[0:1], vcc
	s_cbranch_execz .LBB0_1454
	s_waitcnt lgkmcnt(0)
	v_add_f32_e32 v122, v122, v123
	global_atomic_add_f32 v[112:113], v122, off
.LBB0_1454:
	s_or_b64 exec, exec, s[0:1]
	v_add_u32_e32 v122, 16, v140
	s_waitcnt lgkmcnt(0)
	v_ashrrev_i32_e32 v123, 31, v122
	v_lshlrev_b64 v[148:149], 12, v[122:123]
	v_lshl_add_u64 v[148:149], s[62:63], 0, v[148:149]
	v_lshl_add_u64 v[152:153], v[142:143], 1, v[148:149]
	s_nop 0
	s_nop 0
	s_nop 0
	s_waitcnt vmcnt(11)
	v_lshlrev_b32_e32 v156, 16, v198
	v_and_b32_e32 v157, 0xffff0000, v198
	v_lshlrev_b32_e32 v148, 16, v199
	v_and_b32_e32 v149, 0xffff0000, v199
	s_waitcnt vmcnt(10)
	v_lshlrev_b32_e32 v174, 16, v202
	v_and_b32_e32 v175, 0xffff0000, v202
	v_lshlrev_b32_e32 v152, 16, v203
	v_and_b32_e32 v153, 0xffff0000, v203
	v_lshlrev_b32_e32 v158, 16, v200
	v_and_b32_e32 v159, 0xffff0000, v200
	v_lshlrev_b32_e32 v176, 16, v204
	v_and_b32_e32 v177, 0xffff0000, v204
	v_pk_add_f32 v[110:111], v[110:111], v[148:149]
	v_pk_add_f32 v[148:149], v[108:109], v[156:157]
	v_pk_add_f32 v[102:103], v[102:103], v[152:153]
	v_pk_add_f32 v[100:101], v[100:101], v[174:175]
	v_lshlrev_b32_e32 v150, 16, v201
	v_and_b32_e32 v151, 0xffff0000, v201
	v_lshlrev_b32_e32 v154, 16, v205
	v_and_b32_e32 v155, 0xffff0000, v205
	v_pk_add_f32 v[108:109], v[104:105], v[158:159]
	v_pk_add_f32 v[96:97], v[96:97], v[176:177]
	v_mul_f32_e32 v104, v149, v149
	v_mul_f32_e32 v105, v111, v111
	v_mul_f32_e32 v152, v101, v101
	v_mul_f32_e32 v153, v103, v103
	v_pk_add_f32 v[106:107], v[106:107], v[150:151]
	v_pk_add_f32 v[98:99], v[98:99], v[154:155]
	v_mul_f32_e32 v150, v109, v109
	v_mul_f32_e32 v154, v97, v97
	v_fmac_f32_e32 v104, v148, v148
	v_fmac_f32_e32 v105, v110, v110
	v_fmac_f32_e32 v152, v100, v100
	v_fmac_f32_e32 v153, v102, v102
	v_mul_f32_e32 v151, v107, v107
	v_mul_f32_e32 v155, v99, v99
	v_fmac_f32_e32 v150, v108, v108
	v_fmac_f32_e32 v154, v96, v96
	v_add_f32_e32 v104, v104, v105
	v_add_f32_e32 v105, v152, v153
	v_fmac_f32_e32 v151, v106, v106
	v_fmac_f32_e32 v155, v98, v98
	v_add_f32_e32 v104, v150, v104
	v_add_f32_e32 v105, v154, v105
	v_add_f32_e32 v104, v151, v104
	v_add_f32_e32 v105, v155, v105
	v_add_f32_e32 v104, v104, v105
	ds_bpermute_b32 v105, v172, v104
	s_waitcnt lgkmcnt(0)
	v_add_f32_e32 v104, v104, v105
	ds_bpermute_b32 v105, v173, v104
	s_and_saveexec_b64 s[0:1], vcc
	s_cbranch_execz .LBB0_1456
	v_lshl_add_u64 v[150:151], v[122:123], 2, s[6:7]
	s_waitcnt lgkmcnt(0)
	v_add_f32_e32 v104, v104, v105
	global_atomic_add_f32 v[150:151], v104, off
.LBB0_1456:
	s_or_b64 exec, exec, s[0:1]
	v_add_u32_e32 v104, 32, v140
	s_waitcnt lgkmcnt(0)
	v_ashrrev_i32_e32 v105, 31, v104
	v_lshlrev_b64 v[150:151], 12, v[104:105]
	v_lshl_add_u64 v[150:151], s[62:63], 0, v[150:151]
	v_lshl_add_u64 v[154:155], v[142:143], 1, v[150:151]
	s_nop 0
	s_nop 0
	s_nop 0
	s_waitcnt vmcnt(9)
	v_lshlrev_b32_e32 v158, 16, v206
	v_and_b32_e32 v159, 0xffff0000, v206
	v_lshlrev_b32_e32 v150, 16, v207
	v_and_b32_e32 v151, 0xffff0000, v207
	s_waitcnt vmcnt(8)
	v_lshlrev_b32_e32 v176, 16, v210
	v_and_b32_e32 v177, 0xffff0000, v210
	v_lshlrev_b32_e32 v154, 16, v211
	v_and_b32_e32 v155, 0xffff0000, v211
	v_lshlrev_b32_e32 v174, 16, v208
	v_and_b32_e32 v175, 0xffff0000, v208
	v_lshlrev_b32_e32 v178, 16, v212
	v_and_b32_e32 v179, 0xffff0000, v212
	v_pk_add_f32 v[94:95], v[94:95], v[150:151]
	v_pk_add_f32 v[150:151], v[92:93], v[158:159]
	v_pk_add_f32 v[86:87], v[86:87], v[154:155]
	v_pk_add_f32 v[84:85], v[84:85], v[176:177]
	v_lshlrev_b32_e32 v152, 16, v209
	v_and_b32_e32 v153, 0xffff0000, v209
	v_lshlrev_b32_e32 v156, 16, v213
	v_and_b32_e32 v157, 0xffff0000, v213
	v_pk_add_f32 v[92:93], v[88:89], v[174:175]
	v_pk_add_f32 v[80:81], v[80:81], v[178:179]
	v_mul_f32_e32 v88, v151, v151
	v_mul_f32_e32 v89, v95, v95
	v_mul_f32_e32 v154, v85, v85
	v_mul_f32_e32 v155, v87, v87
	v_pk_add_f32 v[90:91], v[90:91], v[152:153]
	v_pk_add_f32 v[82:83], v[82:83], v[156:157]
	v_mul_f32_e32 v152, v93, v93
	v_mul_f32_e32 v156, v81, v81
	v_fmac_f32_e32 v88, v150, v150
	v_fmac_f32_e32 v89, v94, v94
	v_fmac_f32_e32 v154, v84, v84
	v_fmac_f32_e32 v155, v86, v86
	v_mul_f32_e32 v153, v91, v91
	v_mul_f32_e32 v157, v83, v83
	v_fmac_f32_e32 v152, v92, v92
	v_fmac_f32_e32 v156, v80, v80
	v_add_f32_e32 v88, v88, v89
	v_add_f32_e32 v89, v154, v155
	v_fmac_f32_e32 v153, v90, v90
	v_fmac_f32_e32 v157, v82, v82
	v_add_f32_e32 v88, v152, v88
	v_add_f32_e32 v89, v156, v89
	v_add_f32_e32 v88, v153, v88
	v_add_f32_e32 v89, v157, v89
	v_add_f32_e32 v88, v88, v89
	ds_bpermute_b32 v89, v172, v88
	s_waitcnt lgkmcnt(0)
	v_add_f32_e32 v88, v88, v89
	ds_bpermute_b32 v89, v173, v88
	s_and_saveexec_b64 s[0:1], vcc
	s_cbranch_execz .LBB0_1458
	v_lshl_add_u64 v[152:153], v[104:105], 2, s[6:7]
	s_waitcnt lgkmcnt(0)
	v_add_f32_e32 v88, v88, v89
	global_atomic_add_f32 v[152:153], v88, off
.LBB0_1458:
	s_or_b64 exec, exec, s[0:1]
	v_add_u32_e32 v88, 48, v140
	s_waitcnt lgkmcnt(0)
	v_ashrrev_i32_e32 v89, 31, v88
	v_lshlrev_b64 v[152:153], 12, v[88:89]
	v_lshl_add_u64 v[152:153], s[62:63], 0, v[152:153]
	v_lshl_add_u64 v[156:157], v[142:143], 1, v[152:153]
	s_nop 0
	s_nop 0
	s_nop 0
	s_waitcnt vmcnt(7)
	v_lshlrev_b32_e32 v174, 16, v214
	v_and_b32_e32 v175, 0xffff0000, v214
	v_lshlrev_b32_e32 v152, 16, v215
	v_and_b32_e32 v153, 0xffff0000, v215
	s_waitcnt vmcnt(6)
	v_lshlrev_b32_e32 v178, 16, v218
	v_and_b32_e32 v179, 0xffff0000, v218
	v_lshlrev_b32_e32 v156, 16, v219
	v_and_b32_e32 v157, 0xffff0000, v219
	v_lshlrev_b32_e32 v176, 16, v216
	v_and_b32_e32 v177, 0xffff0000, v216
	v_lshlrev_b32_e32 v180, 16, v220
	v_and_b32_e32 v181, 0xffff0000, v220
	v_pk_add_f32 v[78:79], v[78:79], v[152:153]
	v_pk_add_f32 v[152:153], v[76:77], v[174:175]
	v_pk_add_f32 v[70:71], v[70:71], v[156:157]
	v_pk_add_f32 v[68:69], v[68:69], v[178:179]
	v_lshlrev_b32_e32 v154, 16, v217
	v_and_b32_e32 v155, 0xffff0000, v217
	v_lshlrev_b32_e32 v158, 16, v221
	v_and_b32_e32 v159, 0xffff0000, v221
	v_pk_add_f32 v[76:77], v[72:73], v[176:177]
	v_pk_add_f32 v[64:65], v[64:65], v[180:181]
	v_mul_f32_e32 v72, v153, v153
	v_mul_f32_e32 v73, v79, v79
	v_mul_f32_e32 v156, v69, v69
	v_mul_f32_e32 v157, v71, v71
	v_pk_add_f32 v[74:75], v[74:75], v[154:155]
	v_pk_add_f32 v[66:67], v[66:67], v[158:159]
	v_mul_f32_e32 v154, v77, v77
	v_mul_f32_e32 v158, v65, v65
	v_fmac_f32_e32 v72, v152, v152
	v_fmac_f32_e32 v73, v78, v78
	v_fmac_f32_e32 v156, v68, v68
	v_fmac_f32_e32 v157, v70, v70
	v_mul_f32_e32 v155, v75, v75
	v_mul_f32_e32 v159, v67, v67
	v_fmac_f32_e32 v154, v76, v76
	v_fmac_f32_e32 v158, v64, v64
	v_add_f32_e32 v72, v72, v73
	v_add_f32_e32 v73, v156, v157
	v_fmac_f32_e32 v155, v74, v74
	v_fmac_f32_e32 v159, v66, v66
	v_add_f32_e32 v72, v154, v72
	v_add_f32_e32 v73, v158, v73
	v_add_f32_e32 v72, v155, v72
	v_add_f32_e32 v73, v159, v73
	v_add_f32_e32 v72, v72, v73
	ds_bpermute_b32 v73, v172, v72
	s_waitcnt lgkmcnt(0)
	v_add_f32_e32 v72, v72, v73
	ds_bpermute_b32 v73, v173, v72
	s_and_saveexec_b64 s[0:1], vcc
	s_cbranch_execz .LBB0_1460
	v_lshl_add_u64 v[154:155], v[88:89], 2, s[6:7]
	s_waitcnt lgkmcnt(0)
	v_add_f32_e32 v72, v72, v73
	global_atomic_add_f32 v[154:155], v72, off
.LBB0_1460:
	s_or_b64 exec, exec, s[0:1]
	v_add_u32_e32 v72, 0x80, v140
	s_waitcnt lgkmcnt(0)
	v_ashrrev_i32_e32 v73, 31, v72
	v_lshlrev_b64 v[154:155], 12, v[72:73]
	v_lshl_add_u64 v[154:155], s[62:63], 0, v[154:155]
	v_lshl_add_u64 v[158:159], v[142:143], 1, v[154:155]
	s_nop 0
	s_nop 0
	s_waitcnt vmcnt(5)
	v_lshlrev_b32_e32 v158, 16, v222
	v_and_b32_e32 v159, 0xffff0000, v222
	v_lshlrev_b32_e32 v154, 16, v223
	v_and_b32_e32 v155, 0xffff0000, v223
	s_waitcnt vmcnt(4)
	v_lshlrev_b32_e32 v180, 16, v230
	v_and_b32_e32 v181, 0xffff0000, v230
	v_lshlrev_b32_e32 v174, 16, v231
	v_and_b32_e32 v175, 0xffff0000, v231
	v_lshlrev_b32_e32 v178, 16, v224
	v_and_b32_e32 v179, 0xffff0000, v224
	v_lshlrev_b32_e32 v182, 16, v232
	v_and_b32_e32 v183, 0xffff0000, v232
	v_pk_add_f32 v[62:63], v[62:63], v[154:155]
	v_pk_add_f32 v[154:155], v[60:61], v[158:159]
	v_pk_add_f32 v[54:55], v[54:55], v[174:175]
	v_pk_add_f32 v[52:53], v[52:53], v[180:181]
	v_lshlrev_b32_e32 v156, 16, v225
	v_and_b32_e32 v157, 0xffff0000, v225
	v_lshlrev_b32_e32 v176, 16, v233
	v_and_b32_e32 v177, 0xffff0000, v233
	v_pk_add_f32 v[60:61], v[56:57], v[178:179]
	v_pk_add_f32 v[48:49], v[48:49], v[182:183]
	v_mul_f32_e32 v56, v155, v155
	v_mul_f32_e32 v57, v63, v63
	v_mul_f32_e32 v158, v53, v53
	v_mul_f32_e32 v159, v55, v55
	v_pk_add_f32 v[58:59], v[58:59], v[156:157]
	v_pk_add_f32 v[50:51], v[50:51], v[176:177]
	v_mul_f32_e32 v156, v61, v61
	v_mul_f32_e32 v174, v49, v49
	v_fmac_f32_e32 v56, v154, v154
	v_fmac_f32_e32 v57, v62, v62
	v_fmac_f32_e32 v158, v52, v52
	v_fmac_f32_e32 v159, v54, v54
	v_mul_f32_e32 v157, v59, v59
	v_mul_f32_e32 v175, v51, v51
	v_fmac_f32_e32 v156, v60, v60
	v_fmac_f32_e32 v174, v48, v48
	v_add_f32_e32 v56, v56, v57
	v_add_f32_e32 v57, v158, v159
	v_fmac_f32_e32 v157, v58, v58
	v_fmac_f32_e32 v175, v50, v50
	v_add_f32_e32 v56, v156, v56
	v_add_f32_e32 v57, v174, v57
	v_add_f32_e32 v56, v157, v56
	v_add_f32_e32 v57, v175, v57
	v_add_f32_e32 v56, v56, v57
	ds_bpermute_b32 v57, v172, v56
	s_waitcnt lgkmcnt(0)
	v_add_f32_e32 v56, v56, v57
	ds_bpermute_b32 v57, v173, v56
	s_and_saveexec_b64 s[0:1], vcc
	s_cbranch_execz .LBB0_1462
	v_lshl_add_u64 v[156:157], v[72:73], 2, s[6:7]
	s_waitcnt lgkmcnt(0)
	v_add_f32_e32 v56, v56, v57
	global_atomic_add_f32 v[156:157], v56, off
.LBB0_1462:
	s_or_b64 exec, exec, s[0:1]
	v_add_u32_e32 v56, 0x90, v140
	s_waitcnt lgkmcnt(0)
	v_ashrrev_i32_e32 v57, 31, v56
	v_lshlrev_b64 v[156:157], 12, v[56:57]
	v_lshl_add_u64 v[156:157], s[62:63], 0, v[156:157]
	v_lshl_add_u64 v[174:175], v[142:143], 1, v[156:157]
	s_nop 0
	s_nop 0
	s_nop 0
	s_waitcnt vmcnt(3)
	v_lshlrev_b32_e32 v178, 16, v234
	v_and_b32_e32 v179, 0xffff0000, v234
	v_lshlrev_b32_e32 v156, 16, v235
	v_and_b32_e32 v157, 0xffff0000, v235
	s_waitcnt vmcnt(2)
	v_lshlrev_b32_e32 v182, 16, v238
	v_and_b32_e32 v183, 0xffff0000, v238
	v_lshlrev_b32_e32 v174, 16, v239
	v_and_b32_e32 v175, 0xffff0000, v239
	v_lshlrev_b32_e32 v180, 16, v236
	v_and_b32_e32 v181, 0xffff0000, v236
	v_lshlrev_b32_e32 v184, 16, v240
	v_and_b32_e32 v185, 0xffff0000, v240
	v_pk_add_f32 v[46:47], v[46:47], v[156:157]
	v_pk_add_f32 v[156:157], v[44:45], v[178:179]
	v_pk_add_f32 v[38:39], v[38:39], v[174:175]
	v_pk_add_f32 v[36:37], v[36:37], v[182:183]
	v_lshlrev_b32_e32 v158, 16, v237
	v_and_b32_e32 v159, 0xffff0000, v237
	v_lshlrev_b32_e32 v176, 16, v241
	v_and_b32_e32 v177, 0xffff0000, v241
	v_pk_add_f32 v[44:45], v[40:41], v[180:181]
	v_pk_add_f32 v[32:33], v[32:33], v[184:185]
	v_mul_f32_e32 v40, v157, v157
	v_mul_f32_e32 v41, v47, v47
	v_mul_f32_e32 v174, v37, v37
	v_mul_f32_e32 v175, v39, v39
	v_pk_add_f32 v[42:43], v[42:43], v[158:159]
	v_pk_add_f32 v[34:35], v[34:35], v[176:177]
	v_mul_f32_e32 v158, v45, v45
	v_mul_f32_e32 v176, v33, v33
	v_fmac_f32_e32 v40, v156, v156
	v_fmac_f32_e32 v41, v46, v46
	v_fmac_f32_e32 v174, v36, v36
	v_fmac_f32_e32 v175, v38, v38
	v_mul_f32_e32 v159, v43, v43
	v_mul_f32_e32 v177, v35, v35
	v_fmac_f32_e32 v158, v44, v44
	v_fmac_f32_e32 v176, v32, v32
	v_add_f32_e32 v40, v40, v41
	v_add_f32_e32 v41, v174, v175
	v_fmac_f32_e32 v159, v42, v42
	v_fmac_f32_e32 v177, v34, v34
	v_add_f32_e32 v40, v158, v40
	v_add_f32_e32 v41, v176, v41
	v_add_f32_e32 v40, v159, v40
	v_add_f32_e32 v41, v177, v41
	v_add_f32_e32 v40, v40, v41
	ds_bpermute_b32 v41, v172, v40
	s_waitcnt lgkmcnt(0)
	v_add_f32_e32 v40, v40, v41
	ds_bpermute_b32 v41, v173, v40
	s_and_saveexec_b64 s[0:1], vcc
	s_cbranch_execz .LBB0_1464
	v_lshl_add_u64 v[158:159], v[56:57], 2, s[6:7]
	s_waitcnt lgkmcnt(0)
	v_add_f32_e32 v40, v40, v41
	global_atomic_add_f32 v[158:159], v40, off
.LBB0_1464:
	s_or_b64 exec, exec, s[0:1]
	v_add_u32_e32 v40, 0xa0, v140
	s_waitcnt lgkmcnt(0)
	v_ashrrev_i32_e32 v41, 31, v40
	v_lshlrev_b64 v[158:159], 12, v[40:41]
	v_lshl_add_u64 v[158:159], s[62:63], 0, v[158:159]
	v_lshl_add_u64 v[158:159], v[142:143], 1, v[158:159]
	s_nop 0
	s_nop 0
	s_waitcnt vmcnt(1)
	v_lshlrev_b32_e32 v158, 16, v242
	v_and_b32_e32 v159, 0xffff0000, v242
	v_lshlrev_b32_e32 v174, 16, v243
	v_and_b32_e32 v175, 0xffff0000, v243
	s_waitcnt vmcnt(0)
	v_lshlrev_b32_e32 v184, 16, v246
	v_and_b32_e32 v185, 0xffff0000, v246
	v_lshlrev_b32_e32 v178, 16, v247
	v_and_b32_e32 v179, 0xffff0000, v247
	v_lshlrev_b32_e32 v182, 16, v244
	v_and_b32_e32 v183, 0xffff0000, v244
	v_lshlrev_b32_e32 v176, 16, v245
	v_and_b32_e32 v177, 0xffff0000, v245
	v_lshlrev_b32_e32 v186, 16, v248
	v_and_b32_e32 v187, 0xffff0000, v248
	v_pk_add_f32 v[30:31], v[30:31], v[174:175]
	v_pk_add_f32 v[158:159], v[28:29], v[158:159]
	v_pk_add_f32 v[22:23], v[22:23], v[178:179]
	v_pk_add_f32 v[20:21], v[20:21], v[184:185]
	v_lshlrev_b32_e32 v180, 16, v249
	v_and_b32_e32 v181, 0xffff0000, v249
	v_pk_add_f32 v[26:27], v[26:27], v[176:177]
	v_pk_add_f32 v[28:29], v[24:25], v[182:183]
	v_pk_add_f32 v[16:17], v[16:17], v[186:187]
	v_mul_f32_e32 v24, v159, v159
	v_mul_f32_e32 v25, v31, v31
	v_mul_f32_e32 v176, v21, v21
	v_mul_f32_e32 v177, v23, v23
	v_pk_add_f32 v[18:19], v[18:19], v[180:181]
	v_mul_f32_e32 v174, v29, v29
	v_mul_f32_e32 v178, v17, v17
	v_fmac_f32_e32 v24, v158, v158
	v_fmac_f32_e32 v25, v30, v30
	v_fmac_f32_e32 v176, v20, v20
	v_fmac_f32_e32 v177, v22, v22
	v_mul_f32_e32 v175, v27, v27
	v_mul_f32_e32 v179, v19, v19
	v_fmac_f32_e32 v174, v28, v28
	v_fmac_f32_e32 v178, v16, v16
	v_add_f32_e32 v24, v24, v25
	v_add_f32_e32 v25, v176, v177
	v_fmac_f32_e32 v175, v26, v26
	v_fmac_f32_e32 v179, v18, v18
	v_add_f32_e32 v24, v174, v24
	v_add_f32_e32 v25, v178, v25
	v_add_f32_e32 v24, v175, v24
	v_add_f32_e32 v25, v179, v25
	v_add_f32_e32 v24, v24, v25
	ds_bpermute_b32 v25, v172, v24
	s_waitcnt lgkmcnt(0)
	v_add_f32_e32 v24, v24, v25
	ds_bpermute_b32 v25, v173, v24
	s_and_saveexec_b64 s[0:1], vcc
	s_cbranch_execz .LBB0_1466
	v_lshl_add_u64 v[174:175], v[40:41], 2, s[6:7]
	s_waitcnt lgkmcnt(0)
	v_add_f32_e32 v24, v24, v25
	global_atomic_add_f32 v[174:175], v24, off
